# conv seam fix-up phase (P8) folded into the head of each P9 unit (redundant per-unit repair of the rows it reads + block barrier); one grid barrier fewer
# speedup vs baseline: 1.0167x; 1.0108x over previous
.LBB0_1357:
	s_cmp_lt_i32 s94, 9
	s_cselect_b64 s[0:1], -1, 0
	s_cmp_gt_i32 s95, 8
	s_cselect_b64 s[2:3], -1, 0
	s_and_b64 s[0:1], s[0:1], s[2:3]
	s_andn2_b64 vcc, exec, s[0:1]
	v_readlane_b32 s50, v253, 54
	v_readlane_b32 s51, v253, 55
.LBB0_1417:
	s_cmp_lt_i32 s94, 10
	s_cselect_b64 s[0:1], -1, 0
	s_cmp_gt_i32 s95, 9
	s_cselect_b64 s[2:3], -1, 0
	s_and_b64 s[0:1], s[0:1], s[2:3]
	s_andn2_b64 vcc, exec, s[0:1]
	s_cbranch_vccnz .LBB0_1500
	s_cmpk_lt_i32 s93, 0x100
	v_readfirstlane_b32 s0, v215
	s_cbranch_scc0 .LBB0_1446
	s_ashr_i32 s1, s93, 31
	s_lshr_b32 s1, s1, 25
	s_add_i32 s2, s93, s1
	s_ashr_i32 s1, s2, 7
	s_and_b32 s2, s2, 0xffffff80
	s_sub_i32 s2, s93, s2
	s_cmpk_gt_i32 s2, 0x7f
	s_cbranch_scc1 .LBB0_1421
	s_ashr_i32 s3, s2, 31
	s_lshr_b32 s3, s3, 29
	s_add_i32 s3, s2, s3
	s_ashr_i32 s4, s3, 3
	s_and_b32 s3, s3, -8
	s_sub_i32 s2, s2, s3
	s_lshl_b32 s3, s2, 4
	s_cmp_lt_i32 s2, 0
	s_mul_i32 s2, s2, 17
	s_cselect_b32 s2, s2, s3
	s_add_i32 s2, s2, s4
	s_ashr_i32 s3, s2, 31
	s_lshr_b32 s3, s3, 28
	s_add_i32 s3, s2, s3
	s_ashr_i32 s4, s3, 4
	s_lshl_b32 s4, s4, 2
	s_sub_i32 s5, 32, s4
	s_min_i32 s5, s5, 4
	s_abs_i32 s6, s5
	v_cvt_f32_u32_e32 v0, s6
	s_sub_i32 s8, 0, s6
	s_and_b32 s3, s3, -16
	s_sub_i32 s2, s2, s3
	v_rcp_iflag_f32_e32 v0, v0
	s_abs_i32 s3, s2
	s_xor_b32 s7, s2, s5
	s_ashr_i32 s7, s7, 31
	v_mul_f32_e32 v0, 0x4f7ffffe, v0
	v_cvt_u32_f32_e32 v0, v0
	s_nop 0
	v_readfirstlane_b32 s9, v0
	s_mul_i32 s8, s8, s9
	s_mul_hi_u32 s8, s9, s8
	s_add_i32 s9, s9, s8
	s_mul_hi_u32 s8, s3, s9
	s_mul_i32 s9, s8, s6
	s_sub_i32 s3, s3, s9
	s_add_i32 s10, s8, 1
	s_sub_i32 s9, s3, s6
	s_cmp_ge_u32 s3, s6
	s_cselect_b32 s8, s10, s8
	s_cselect_b32 s3, s9, s3
	s_add_i32 s9, s8, 1
	s_cmp_ge_u32 s3, s6
	s_cselect_b32 s3, s9, s8
	s_xor_b32 s3, s3, s7
	s_sub_i32 s44, s3, s7
	s_mul_i32 s3, s44, s5
	s_sub_i32 s2, s2, s3
	s_add_i32 s45, s4, s2
.LBB0_1421:
	s_mov_b64 s[6:7], exec
	v_cmp_gt_u32_e32 vcc, 0x160, v215
	s_and_b64 exec, exec, vcc
	s_cbranch_execz .Lfx_done
	s_mul_i32 s8, s1, 0x580
	v_lshl_add_u32 v0, v215, 2, s8
	v_lshlrev_b32_e32 v1, 2, v0
	v_add_u32_e32 v2, 0x2c00, v1
	v_add_u32_e32 v3, 0x5800, v1
	v_add_u32_e32 v4, 0x8400, v1
	v_add_u32_e32 v5, 0xb000, v1
	v_add_u32_e32 v6, 0xdc00, v1
	v_add_u32_e32 v7, 0x10800, v1
	v_add_u32_e32 v8, 0x13400, v1
	v_lshlrev_b32_e32 v9, 1, v0
	v_add_u32_e32 v10, 0x1600, v9
	v_readlane_b32 s8, v253, 33
	v_readlane_b32 s9, v253, 34
	v_readlane_b32 s10, v253, 35
	v_readlane_b32 s11, v253, 36
	s_add_u32 s26, s74, 0x8000000
	s_addc_u32 s27, s75, 0
	s_add_u32 s28, s74, 0xc000000
	s_addc_u32 s29, s75, 0
	s_nop 2
	global_load_dwordx4 v[16:19], v1, s[8:9]
	global_load_dwordx4 v[20:23], v2, s[8:9]
	s_add_u32 s12, s8, 0x5800
	s_addc_u32 s13, s9, 0
	global_load_dwordx4 v[24:27], v1, s[12:13]
	global_load_dwordx4 v[28:31], v2, s[12:13]
	s_add_u32 s12, s8, 0xb000
	s_addc_u32 s13, s9, 0
	global_load_dwordx4 v[32:35], v1, s[12:13]
	global_load_dwordx4 v[36:39], v2, s[12:13]
	global_load_dwordx4 v[40:43], v1, s[10:11]
	global_load_dwordx4 v[44:47], v2, s[10:11]
	s_lshl_b32 s18, s45, 8
	s_movk_i32 s12, 0x3ff
	s_cmp_lt_u32 s18, 0x1000
	s_cselect_b32 s19, 0xff, s12
	s_and_b32 s19, s18, s19
	s_cmp_lg_u32 s19, 0
	s_cselect_b32 s19, 1, 0
	s_cmp_lt_u32 s18, 0x2000
	s_cselect_b32 s30, s19, 0
	s_cmp_eq_u32 s30, 0
	s_cbranch_scc1 .Lfx_l0
	s_lshr_b32 s19, s18, 6
	s_mul_i32 s19, s19, 0x16000
	s_add_u32 s20, s26, s19
	s_addc_u32 s21, s27, 0
	s_sub_u32 s20, s20, 0xb000
	s_subb_u32 s21, s21, 0
	global_load_dwordx4 v[48:51], v1, s[20:21]
	global_load_dwordx4 v[52:55], v2, s[20:21]
	global_load_dwordx4 v[56:59], v3, s[20:21]
	global_load_dwordx4 v[60:63], v4, s[20:21]
	global_load_dwordx4 v[64:67], v5, s[20:21]
	global_load_dwordx4 v[68:71], v6, s[20:21]
	global_load_dwordx4 v[72:75], v7, s[20:21]
	global_load_dwordx4 v[76:79], v8, s[20:21]
.Lfx_l0:
	s_lshl_b32 s18, s45, 8
	s_add_i32 s18, s18, 64
	s_movk_i32 s12, 0x3ff
	s_cmp_lt_u32 s18, 0x1000
	s_cselect_b32 s19, 0xff, s12
	s_and_b32 s19, s18, s19
	s_cmp_lg_u32 s19, 0
	s_cselect_b32 s19, 1, 0
	s_cmp_lt_u32 s18, 0x2000
	s_cselect_b32 s31, s19, 0
	s_cmp_eq_u32 s31, 0
	s_cbranch_scc1 .Lfx_l1
	s_lshr_b32 s19, s18, 6
	s_mul_i32 s19, s19, 0x16000
	s_add_u32 s20, s26, s19
	s_addc_u32 s21, s27, 0
	s_sub_u32 s20, s20, 0xb000
	s_subb_u32 s21, s21, 0
	global_load_dwordx4 v[80:83], v1, s[20:21]
	global_load_dwordx4 v[84:87], v2, s[20:21]
	global_load_dwordx4 v[88:91], v3, s[20:21]
	global_load_dwordx4 v[92:95], v4, s[20:21]
	global_load_dwordx4 v[96:99], v5, s[20:21]
	global_load_dwordx4 v[100:103], v6, s[20:21]
	global_load_dwordx4 v[104:107], v7, s[20:21]
	global_load_dwordx4 v[108:111], v8, s[20:21]
.Lfx_l1:
	s_lshl_b32 s18, s45, 8
	s_add_i32 s18, s18, 128
	s_movk_i32 s12, 0x3ff
	s_cmp_lt_u32 s18, 0x1000
	s_cselect_b32 s19, 0xff, s12
	s_and_b32 s19, s18, s19
	s_cmp_lg_u32 s19, 0
	s_cselect_b32 s19, 1, 0
	s_cmp_lt_u32 s18, 0x2000
	s_cselect_b32 s32, s19, 0
	s_cmp_eq_u32 s32, 0
	s_cbranch_scc1 .Lfx_l2
	s_lshr_b32 s19, s18, 6
	s_mul_i32 s19, s19, 0x16000
	s_add_u32 s20, s26, s19
	s_addc_u32 s21, s27, 0
	s_sub_u32 s20, s20, 0xb000
	s_subb_u32 s21, s21, 0
	global_load_dwordx4 v[112:115], v1, s[20:21]
	global_load_dwordx4 v[116:119], v2, s[20:21]
	global_load_dwordx4 v[120:123], v3, s[20:21]
	global_load_dwordx4 v[124:127], v4, s[20:21]
	global_load_dwordx4 v[128:131], v5, s[20:21]
	global_load_dwordx4 v[132:135], v6, s[20:21]
	global_load_dwordx4 v[136:139], v7, s[20:21]
	global_load_dwordx4 v[140:143], v8, s[20:21]
.Lfx_l2:
	s_lshl_b32 s18, s45, 8
	s_add_i32 s18, s18, 192
	s_movk_i32 s12, 0x3ff
	s_cmp_lt_u32 s18, 0x1000
	s_cselect_b32 s19, 0xff, s12
	s_and_b32 s19, s18, s19
	s_cmp_lg_u32 s19, 0
	s_cselect_b32 s19, 1, 0
	s_cmp_lt_u32 s18, 0x2000
	s_cselect_b32 s33, s19, 0
	s_cmp_eq_u32 s33, 0
	s_cbranch_scc1 .Lfx_l3
	s_lshr_b32 s19, s18, 6
	s_mul_i32 s19, s19, 0x16000
	s_add_u32 s20, s26, s19
	s_addc_u32 s21, s27, 0
	s_sub_u32 s20, s20, 0xb000
	s_subb_u32 s21, s21, 0
	global_load_dwordx4 v[144:147], v1, s[20:21]
	global_load_dwordx4 v[148:151], v2, s[20:21]
	global_load_dwordx4 v[152:155], v3, s[20:21]
	global_load_dwordx4 v[156:159], v4, s[20:21]
	global_load_dwordx4 v[160:163], v5, s[20:21]
	global_load_dwordx4 v[164:167], v6, s[20:21]
	global_load_dwordx4 v[168:171], v7, s[20:21]
	global_load_dwordx4 v[172:175], v8, s[20:21]
.Lfx_l3:
	s_lshl_b32 s18, s45, 8
	s_add_i32 s18, s18, 256
	s_movk_i32 s12, 0x3ff
	s_cmp_lt_u32 s18, 0x1000
	s_cselect_b32 s19, 0xff, s12
	s_and_b32 s19, s18, s19
	s_cmp_lg_u32 s19, 0
	s_cselect_b32 s19, 1, 0
	s_cmp_lt_u32 s18, 0x2000
	s_cselect_b32 s34, s19, 0
	s_cmp_eq_u32 s34, 0
	s_cbranch_scc1 .Lfx_l4
	s_lshr_b32 s19, s18, 6
	s_mul_i32 s19, s19, 0x16000
	s_add_u32 s20, s26, s19
	s_addc_u32 s21, s27, 0
	s_sub_u32 s20, s20, 0xb000
	s_subb_u32 s21, s21, 0
	global_load_dwordx4 v[176:179], v1, s[20:21]
	global_load_dwordx4 v[180:183], v2, s[20:21]
	global_load_dwordx4 v[184:187], v3, s[20:21]
	global_load_dwordx4 v[188:191], v4, s[20:21]
	global_load_dwordx4 v[192:195], v5, s[20:21]
	global_load_dwordx4 v[196:199], v6, s[20:21]
	global_load_dwordx4 v[200:203], v7, s[20:21]
	global_load_dwordx4 v[204:207], v8, s[20:21]
.Lfx_l4:
	v_mov_b32_e32 v222, 0xbfb8aa3b
	v_mov_b32_e32 v223, 0xbfb8aa3b
	s_waitcnt vmcnt(0)
	s_cmp_eq_u32 s30, 0
	s_cbranch_scc1 .Lfx_c0
	s_lshl_b32 s18, s45, 8
	s_add_i32 s18, s18, -1
	s_mul_i32 s19, s18, 0x1600
	s_add_u32 s22, s28, s19
	s_addc_u32 s23, s29, 0
	v_pk_fma_f32 v[208:209], v[48:49], v[16:17], v[40:41]
	v_pk_fma_f32 v[210:211], v[50:51], v[18:19], v[42:43]
	v_pk_fma_f32 v[208:209], v[56:57], v[24:25], v[208:209]
	v_pk_fma_f32 v[210:211], v[58:59], v[26:27], v[210:211]
	v_pk_fma_f32 v[208:209], v[64:65], v[32:33], v[208:209]
	v_pk_fma_f32 v[210:211], v[66:67], v[34:35], v[210:211]
	v_pk_fma_f32 v[12:13], v[52:53], v[20:21], v[44:45]
	v_pk_fma_f32 v[14:15], v[54:55], v[22:23], v[46:47]
	v_pk_fma_f32 v[12:13], v[60:61], v[28:29], v[12:13]
	v_pk_fma_f32 v[14:15], v[62:63], v[30:31], v[14:15]
	v_pk_fma_f32 v[12:13], v[68:69], v[36:37], v[12:13]
	v_pk_fma_f32 v[14:15], v[70:71], v[38:39], v[14:15]
	v_pk_mul_f32 v[216:217], v[208:209], v[222:223]
	v_pk_mul_f32 v[218:219], v[210:211], v[222:223]
	v_exp_f32_e32 v216, v216
	v_exp_f32_e32 v217, v217
	v_exp_f32_e32 v218, v218
	v_exp_f32_e32 v219, v219
	v_pk_add_f32 v[216:217], v[216:217], 1.0 op_sel_hi:[1,0]
	v_pk_add_f32 v[218:219], v[218:219], 1.0 op_sel_hi:[1,0]
	v_rcp_f32_e32 v216, v216
	v_rcp_f32_e32 v217, v217
	v_rcp_f32_e32 v218, v218
	v_rcp_f32_e32 v219, v219
	v_pk_mul_f32 v[208:209], v[208:209], v[216:217]
	v_pk_mul_f32 v[210:211], v[210:211], v[218:219]
	v_pk_mul_f32 v[208:209], v[208:209], v[12:13]
	v_pk_mul_f32 v[210:211], v[210:211], v[14:15]
	v_cvt_pk_bf16_f32 v224, v208, v209
	v_cvt_pk_bf16_f32 v225, v210, v211
	global_store_dwordx2 v9, v[224:225], s[22:23]
	v_pk_fma_f32 v[208:209], v[56:57], v[16:17], v[40:41]
	v_pk_fma_f32 v[210:211], v[58:59], v[18:19], v[42:43]
	v_pk_fma_f32 v[208:209], v[64:65], v[24:25], v[208:209]
	v_pk_fma_f32 v[210:211], v[66:67], v[26:27], v[210:211]
	v_pk_fma_f32 v[208:209], v[72:73], v[32:33], v[208:209]
	v_pk_fma_f32 v[210:211], v[74:75], v[34:35], v[210:211]
	v_pk_fma_f32 v[12:13], v[60:61], v[20:21], v[44:45]
	v_pk_fma_f32 v[14:15], v[62:63], v[22:23], v[46:47]
	v_pk_fma_f32 v[12:13], v[68:69], v[28:29], v[12:13]
	v_pk_fma_f32 v[14:15], v[70:71], v[30:31], v[14:15]
	v_pk_fma_f32 v[12:13], v[76:77], v[36:37], v[12:13]
	v_pk_fma_f32 v[14:15], v[78:79], v[38:39], v[14:15]
	v_pk_mul_f32 v[216:217], v[208:209], v[222:223]
	v_pk_mul_f32 v[218:219], v[210:211], v[222:223]
	v_exp_f32_e32 v216, v216
	v_exp_f32_e32 v217, v217
	v_exp_f32_e32 v218, v218
	v_exp_f32_e32 v219, v219
	v_pk_add_f32 v[216:217], v[216:217], 1.0 op_sel_hi:[1,0]
	v_pk_add_f32 v[218:219], v[218:219], 1.0 op_sel_hi:[1,0]
	v_rcp_f32_e32 v216, v216
	v_rcp_f32_e32 v217, v217
	v_rcp_f32_e32 v218, v218
	v_rcp_f32_e32 v219, v219
	v_pk_mul_f32 v[208:209], v[208:209], v[216:217]
	v_pk_mul_f32 v[210:211], v[210:211], v[218:219]
	v_pk_mul_f32 v[208:209], v[208:209], v[12:13]
	v_pk_mul_f32 v[210:211], v[210:211], v[14:15]
	v_cvt_pk_bf16_f32 v226, v208, v209
	v_cvt_pk_bf16_f32 v227, v210, v211
	global_store_dwordx2 v10, v[226:227], s[22:23]
.Lfx_c0:
	s_cmp_eq_u32 s31, 0
	s_cbranch_scc1 .Lfx_c1
	s_lshl_b32 s18, s45, 8
	s_add_i32 s18, s18, 63
	s_mul_i32 s19, s18, 0x1600
	s_add_u32 s22, s28, s19
	s_addc_u32 s23, s29, 0
	v_pk_fma_f32 v[208:209], v[80:81], v[16:17], v[40:41]
	v_pk_fma_f32 v[210:211], v[82:83], v[18:19], v[42:43]
	v_pk_fma_f32 v[208:209], v[88:89], v[24:25], v[208:209]
	v_pk_fma_f32 v[210:211], v[90:91], v[26:27], v[210:211]
	v_pk_fma_f32 v[208:209], v[96:97], v[32:33], v[208:209]
	v_pk_fma_f32 v[210:211], v[98:99], v[34:35], v[210:211]
	v_pk_fma_f32 v[12:13], v[84:85], v[20:21], v[44:45]
	v_pk_fma_f32 v[14:15], v[86:87], v[22:23], v[46:47]
	v_pk_fma_f32 v[12:13], v[92:93], v[28:29], v[12:13]
	v_pk_fma_f32 v[14:15], v[94:95], v[30:31], v[14:15]
	v_pk_fma_f32 v[12:13], v[100:101], v[36:37], v[12:13]
	v_pk_fma_f32 v[14:15], v[102:103], v[38:39], v[14:15]
	v_pk_mul_f32 v[216:217], v[208:209], v[222:223]
	v_pk_mul_f32 v[218:219], v[210:211], v[222:223]
	v_exp_f32_e32 v216, v216
	v_exp_f32_e32 v217, v217
	v_exp_f32_e32 v218, v218
	v_exp_f32_e32 v219, v219
	v_pk_add_f32 v[216:217], v[216:217], 1.0 op_sel_hi:[1,0]
	v_pk_add_f32 v[218:219], v[218:219], 1.0 op_sel_hi:[1,0]
	v_rcp_f32_e32 v216, v216
	v_rcp_f32_e32 v217, v217
	v_rcp_f32_e32 v218, v218
	v_rcp_f32_e32 v219, v219
	v_pk_mul_f32 v[208:209], v[208:209], v[216:217]
	v_pk_mul_f32 v[210:211], v[210:211], v[218:219]
	v_pk_mul_f32 v[208:209], v[208:209], v[12:13]
	v_pk_mul_f32 v[210:211], v[210:211], v[14:15]
	v_cvt_pk_bf16_f32 v224, v208, v209
	v_cvt_pk_bf16_f32 v225, v210, v211
	global_store_dwordx2 v9, v[224:225], s[22:23]
	v_pk_fma_f32 v[208:209], v[88:89], v[16:17], v[40:41]
	v_pk_fma_f32 v[210:211], v[90:91], v[18:19], v[42:43]
	v_pk_fma_f32 v[208:209], v[96:97], v[24:25], v[208:209]
	v_pk_fma_f32 v[210:211], v[98:99], v[26:27], v[210:211]
	v_pk_fma_f32 v[208:209], v[104:105], v[32:33], v[208:209]
	v_pk_fma_f32 v[210:211], v[106:107], v[34:35], v[210:211]
	v_pk_fma_f32 v[12:13], v[92:93], v[20:21], v[44:45]
	v_pk_fma_f32 v[14:15], v[94:95], v[22:23], v[46:47]
	v_pk_fma_f32 v[12:13], v[100:101], v[28:29], v[12:13]
	v_pk_fma_f32 v[14:15], v[102:103], v[30:31], v[14:15]
	v_pk_fma_f32 v[12:13], v[108:109], v[36:37], v[12:13]
	v_pk_fma_f32 v[14:15], v[110:111], v[38:39], v[14:15]
	v_pk_mul_f32 v[216:217], v[208:209], v[222:223]
	v_pk_mul_f32 v[218:219], v[210:211], v[222:223]
	v_exp_f32_e32 v216, v216
	v_exp_f32_e32 v217, v217
	v_exp_f32_e32 v218, v218
	v_exp_f32_e32 v219, v219
	v_pk_add_f32 v[216:217], v[216:217], 1.0 op_sel_hi:[1,0]
	v_pk_add_f32 v[218:219], v[218:219], 1.0 op_sel_hi:[1,0]
	v_rcp_f32_e32 v216, v216
	v_rcp_f32_e32 v217, v217
	v_rcp_f32_e32 v218, v218
	v_rcp_f32_e32 v219, v219
	v_pk_mul_f32 v[208:209], v[208:209], v[216:217]
	v_pk_mul_f32 v[210:211], v[210:211], v[218:219]
	v_pk_mul_f32 v[208:209], v[208:209], v[12:13]
	v_pk_mul_f32 v[210:211], v[210:211], v[14:15]
	v_cvt_pk_bf16_f32 v226, v208, v209
	v_cvt_pk_bf16_f32 v227, v210, v211
	global_store_dwordx2 v10, v[226:227], s[22:23]
.Lfx_c1:
	s_cmp_eq_u32 s32, 0
	s_cbranch_scc1 .Lfx_c2
	s_lshl_b32 s18, s45, 8
	s_add_i32 s18, s18, 127
	s_mul_i32 s19, s18, 0x1600
	s_add_u32 s22, s28, s19
	s_addc_u32 s23, s29, 0
	v_pk_fma_f32 v[208:209], v[112:113], v[16:17], v[40:41]
	v_pk_fma_f32 v[210:211], v[114:115], v[18:19], v[42:43]
	v_pk_fma_f32 v[208:209], v[120:121], v[24:25], v[208:209]
	v_pk_fma_f32 v[210:211], v[122:123], v[26:27], v[210:211]
	v_pk_fma_f32 v[208:209], v[128:129], v[32:33], v[208:209]
	v_pk_fma_f32 v[210:211], v[130:131], v[34:35], v[210:211]
	v_pk_fma_f32 v[12:13], v[116:117], v[20:21], v[44:45]
	v_pk_fma_f32 v[14:15], v[118:119], v[22:23], v[46:47]
	v_pk_fma_f32 v[12:13], v[124:125], v[28:29], v[12:13]
	v_pk_fma_f32 v[14:15], v[126:127], v[30:31], v[14:15]
	v_pk_fma_f32 v[12:13], v[132:133], v[36:37], v[12:13]
	v_pk_fma_f32 v[14:15], v[134:135], v[38:39], v[14:15]
	v_pk_mul_f32 v[216:217], v[208:209], v[222:223]
	v_pk_mul_f32 v[218:219], v[210:211], v[222:223]
	v_exp_f32_e32 v216, v216
	v_exp_f32_e32 v217, v217
	v_exp_f32_e32 v218, v218
	v_exp_f32_e32 v219, v219
	v_pk_add_f32 v[216:217], v[216:217], 1.0 op_sel_hi:[1,0]
	v_pk_add_f32 v[218:219], v[218:219], 1.0 op_sel_hi:[1,0]
	v_rcp_f32_e32 v216, v216
	v_rcp_f32_e32 v217, v217
	v_rcp_f32_e32 v218, v218
	v_rcp_f32_e32 v219, v219
	v_pk_mul_f32 v[208:209], v[208:209], v[216:217]
	v_pk_mul_f32 v[210:211], v[210:211], v[218:219]
	v_pk_mul_f32 v[208:209], v[208:209], v[12:13]
	v_pk_mul_f32 v[210:211], v[210:211], v[14:15]
	v_cvt_pk_bf16_f32 v224, v208, v209
	v_cvt_pk_bf16_f32 v225, v210, v211
	global_store_dwordx2 v9, v[224:225], s[22:23]
	v_pk_fma_f32 v[208:209], v[120:121], v[16:17], v[40:41]
	v_pk_fma_f32 v[210:211], v[122:123], v[18:19], v[42:43]
	v_pk_fma_f32 v[208:209], v[128:129], v[24:25], v[208:209]
	v_pk_fma_f32 v[210:211], v[130:131], v[26:27], v[210:211]
	v_pk_fma_f32 v[208:209], v[136:137], v[32:33], v[208:209]
	v_pk_fma_f32 v[210:211], v[138:139], v[34:35], v[210:211]
	v_pk_fma_f32 v[12:13], v[124:125], v[20:21], v[44:45]
	v_pk_fma_f32 v[14:15], v[126:127], v[22:23], v[46:47]
	v_pk_fma_f32 v[12:13], v[132:133], v[28:29], v[12:13]
	v_pk_fma_f32 v[14:15], v[134:135], v[30:31], v[14:15]
	v_pk_fma_f32 v[12:13], v[140:141], v[36:37], v[12:13]
	v_pk_fma_f32 v[14:15], v[142:143], v[38:39], v[14:15]
	v_pk_mul_f32 v[216:217], v[208:209], v[222:223]
	v_pk_mul_f32 v[218:219], v[210:211], v[222:223]
	v_exp_f32_e32 v216, v216
	v_exp_f32_e32 v217, v217
	v_exp_f32_e32 v218, v218
	v_exp_f32_e32 v219, v219
	v_pk_add_f32 v[216:217], v[216:217], 1.0 op_sel_hi:[1,0]
	v_pk_add_f32 v[218:219], v[218:219], 1.0 op_sel_hi:[1,0]
	v_rcp_f32_e32 v216, v216
	v_rcp_f32_e32 v217, v217
	v_rcp_f32_e32 v218, v218
	v_rcp_f32_e32 v219, v219
	v_pk_mul_f32 v[208:209], v[208:209], v[216:217]
	v_pk_mul_f32 v[210:211], v[210:211], v[218:219]
	v_pk_mul_f32 v[208:209], v[208:209], v[12:13]
	v_pk_mul_f32 v[210:211], v[210:211], v[14:15]
	v_cvt_pk_bf16_f32 v226, v208, v209
	v_cvt_pk_bf16_f32 v227, v210, v211
	global_store_dwordx2 v10, v[226:227], s[22:23]
.Lfx_c2:
	s_cmp_eq_u32 s33, 0
	s_cbranch_scc1 .Lfx_c3
	s_lshl_b32 s18, s45, 8
	s_add_i32 s18, s18, 191
	s_mul_i32 s19, s18, 0x1600
	s_add_u32 s22, s28, s19
	s_addc_u32 s23, s29, 0
	v_pk_fma_f32 v[208:209], v[144:145], v[16:17], v[40:41]
	v_pk_fma_f32 v[210:211], v[146:147], v[18:19], v[42:43]
	v_pk_fma_f32 v[208:209], v[152:153], v[24:25], v[208:209]
	v_pk_fma_f32 v[210:211], v[154:155], v[26:27], v[210:211]
	v_pk_fma_f32 v[208:209], v[160:161], v[32:33], v[208:209]
	v_pk_fma_f32 v[210:211], v[162:163], v[34:35], v[210:211]
	v_pk_fma_f32 v[12:13], v[148:149], v[20:21], v[44:45]
	v_pk_fma_f32 v[14:15], v[150:151], v[22:23], v[46:47]
	v_pk_fma_f32 v[12:13], v[156:157], v[28:29], v[12:13]
	v_pk_fma_f32 v[14:15], v[158:159], v[30:31], v[14:15]
	v_pk_fma_f32 v[12:13], v[164:165], v[36:37], v[12:13]
	v_pk_fma_f32 v[14:15], v[166:167], v[38:39], v[14:15]
	v_pk_mul_f32 v[216:217], v[208:209], v[222:223]
	v_pk_mul_f32 v[218:219], v[210:211], v[222:223]
	v_exp_f32_e32 v216, v216
	v_exp_f32_e32 v217, v217
	v_exp_f32_e32 v218, v218
	v_exp_f32_e32 v219, v219
	v_pk_add_f32 v[216:217], v[216:217], 1.0 op_sel_hi:[1,0]
	v_pk_add_f32 v[218:219], v[218:219], 1.0 op_sel_hi:[1,0]
	v_rcp_f32_e32 v216, v216
	v_rcp_f32_e32 v217, v217
	v_rcp_f32_e32 v218, v218
	v_rcp_f32_e32 v219, v219
	v_pk_mul_f32 v[208:209], v[208:209], v[216:217]
	v_pk_mul_f32 v[210:211], v[210:211], v[218:219]
	v_pk_mul_f32 v[208:209], v[208:209], v[12:13]
	v_pk_mul_f32 v[210:211], v[210:211], v[14:15]
	v_cvt_pk_bf16_f32 v224, v208, v209
	v_cvt_pk_bf16_f32 v225, v210, v211
	global_store_dwordx2 v9, v[224:225], s[22:23]
	v_pk_fma_f32 v[208:209], v[152:153], v[16:17], v[40:41]
	v_pk_fma_f32 v[210:211], v[154:155], v[18:19], v[42:43]
	v_pk_fma_f32 v[208:209], v[160:161], v[24:25], v[208:209]
	v_pk_fma_f32 v[210:211], v[162:163], v[26:27], v[210:211]
	v_pk_fma_f32 v[208:209], v[168:169], v[32:33], v[208:209]
	v_pk_fma_f32 v[210:211], v[170:171], v[34:35], v[210:211]
	v_pk_fma_f32 v[12:13], v[156:157], v[20:21], v[44:45]
	v_pk_fma_f32 v[14:15], v[158:159], v[22:23], v[46:47]
	v_pk_fma_f32 v[12:13], v[164:165], v[28:29], v[12:13]
	v_pk_fma_f32 v[14:15], v[166:167], v[30:31], v[14:15]
	v_pk_fma_f32 v[12:13], v[172:173], v[36:37], v[12:13]
	v_pk_fma_f32 v[14:15], v[174:175], v[38:39], v[14:15]
	v_pk_mul_f32 v[216:217], v[208:209], v[222:223]
	v_pk_mul_f32 v[218:219], v[210:211], v[222:223]
	v_exp_f32_e32 v216, v216
	v_exp_f32_e32 v217, v217
	v_exp_f32_e32 v218, v218
	v_exp_f32_e32 v219, v219
	v_pk_add_f32 v[216:217], v[216:217], 1.0 op_sel_hi:[1,0]
	v_pk_add_f32 v[218:219], v[218:219], 1.0 op_sel_hi:[1,0]
	v_rcp_f32_e32 v216, v216
	v_rcp_f32_e32 v217, v217
	v_rcp_f32_e32 v218, v218
	v_rcp_f32_e32 v219, v219
	v_pk_mul_f32 v[208:209], v[208:209], v[216:217]
	v_pk_mul_f32 v[210:211], v[210:211], v[218:219]
	v_pk_mul_f32 v[208:209], v[208:209], v[12:13]
	v_pk_mul_f32 v[210:211], v[210:211], v[14:15]
	v_cvt_pk_bf16_f32 v226, v208, v209
	v_cvt_pk_bf16_f32 v227, v210, v211
	global_store_dwordx2 v10, v[226:227], s[22:23]
.Lfx_c3:
	s_cmp_eq_u32 s34, 0
	s_cbranch_scc1 .Lfx_c4
	s_lshl_b32 s18, s45, 8
	s_add_i32 s18, s18, 255
	s_mul_i32 s19, s18, 0x1600
	s_add_u32 s22, s28, s19
	s_addc_u32 s23, s29, 0
	v_pk_fma_f32 v[208:209], v[176:177], v[16:17], v[40:41]
	v_pk_fma_f32 v[210:211], v[178:179], v[18:19], v[42:43]
	v_pk_fma_f32 v[208:209], v[184:185], v[24:25], v[208:209]
	v_pk_fma_f32 v[210:211], v[186:187], v[26:27], v[210:211]
	v_pk_fma_f32 v[208:209], v[192:193], v[32:33], v[208:209]
	v_pk_fma_f32 v[210:211], v[194:195], v[34:35], v[210:211]
	v_pk_fma_f32 v[12:13], v[180:181], v[20:21], v[44:45]
	v_pk_fma_f32 v[14:15], v[182:183], v[22:23], v[46:47]
	v_pk_fma_f32 v[12:13], v[188:189], v[28:29], v[12:13]
	v_pk_fma_f32 v[14:15], v[190:191], v[30:31], v[14:15]
	v_pk_fma_f32 v[12:13], v[196:197], v[36:37], v[12:13]
	v_pk_fma_f32 v[14:15], v[198:199], v[38:39], v[14:15]
	v_pk_mul_f32 v[216:217], v[208:209], v[222:223]
	v_pk_mul_f32 v[218:219], v[210:211], v[222:223]
	v_exp_f32_e32 v216, v216
	v_exp_f32_e32 v217, v217
	v_exp_f32_e32 v218, v218
	v_exp_f32_e32 v219, v219
	v_pk_add_f32 v[216:217], v[216:217], 1.0 op_sel_hi:[1,0]
	v_pk_add_f32 v[218:219], v[218:219], 1.0 op_sel_hi:[1,0]
	v_rcp_f32_e32 v216, v216
	v_rcp_f32_e32 v217, v217
	v_rcp_f32_e32 v218, v218
	v_rcp_f32_e32 v219, v219
	v_pk_mul_f32 v[208:209], v[208:209], v[216:217]
	v_pk_mul_f32 v[210:211], v[210:211], v[218:219]
	v_pk_mul_f32 v[208:209], v[208:209], v[12:13]
	v_pk_mul_f32 v[210:211], v[210:211], v[14:15]
	v_cvt_pk_bf16_f32 v224, v208, v209
	v_cvt_pk_bf16_f32 v225, v210, v211
	global_store_dwordx2 v9, v[224:225], s[22:23]
	v_pk_fma_f32 v[208:209], v[184:185], v[16:17], v[40:41]
	v_pk_fma_f32 v[210:211], v[186:187], v[18:19], v[42:43]
	v_pk_fma_f32 v[208:209], v[192:193], v[24:25], v[208:209]
	v_pk_fma_f32 v[210:211], v[194:195], v[26:27], v[210:211]
	v_pk_fma_f32 v[208:209], v[200:201], v[32:33], v[208:209]
	v_pk_fma_f32 v[210:211], v[202:203], v[34:35], v[210:211]
	v_pk_fma_f32 v[12:13], v[188:189], v[20:21], v[44:45]
	v_pk_fma_f32 v[14:15], v[190:191], v[22:23], v[46:47]
	v_pk_fma_f32 v[12:13], v[196:197], v[28:29], v[12:13]
	v_pk_fma_f32 v[14:15], v[198:199], v[30:31], v[14:15]
	v_pk_fma_f32 v[12:13], v[204:205], v[36:37], v[12:13]
	v_pk_fma_f32 v[14:15], v[206:207], v[38:39], v[14:15]
	v_pk_mul_f32 v[216:217], v[208:209], v[222:223]
	v_pk_mul_f32 v[218:219], v[210:211], v[222:223]
	v_exp_f32_e32 v216, v216
	v_exp_f32_e32 v217, v217
	v_exp_f32_e32 v218, v218
	v_exp_f32_e32 v219, v219
	v_pk_add_f32 v[216:217], v[216:217], 1.0 op_sel_hi:[1,0]
	v_pk_add_f32 v[218:219], v[218:219], 1.0 op_sel_hi:[1,0]
	v_rcp_f32_e32 v216, v216
	v_rcp_f32_e32 v217, v217
	v_rcp_f32_e32 v218, v218
	v_rcp_f32_e32 v219, v219
	v_pk_mul_f32 v[208:209], v[208:209], v[216:217]
	v_pk_mul_f32 v[210:211], v[210:211], v[218:219]
	v_pk_mul_f32 v[208:209], v[208:209], v[12:13]
	v_pk_mul_f32 v[210:211], v[210:211], v[14:15]
	v_cvt_pk_bf16_f32 v226, v208, v209
	v_cvt_pk_bf16_f32 v227, v210, v211
	global_store_dwordx2 v10, v[226:227], s[22:23]
.Lfx_c4:
.Lfx_done:
	s_mov_b64 exec, s[6:7]
	s_waitcnt vmcnt(0)
	s_barrier
	v_lshlrev_b32_e32 v2, 4, v215
	v_and_b32_e32 v0, 32, v215
	v_bitop3_b32 v1, v2, v0, 48 bitop3:0x6c
	s_waitcnt vmcnt(0)
	v_and_b32_e32 v10, 64, v215
	v_or_b32_e32 v0, v1, v10
	v_lshrrev_b32_e32 v4, 1, v0
	v_lshrrev_b32_e32 v0, 1, v215
	v_lshrrev_b32_e32 v5, 5, v215
	v_and_b32_e32 v0, 24, v0
	v_and_b32_e32 v5, 4, v5
	v_bfe_u32 v6, v215, 2, 2
	s_add_u32 s26, s74, 0xc000000
	v_bfe_u32 v3, v215, 2, 4
	v_or3_b32 v5, v5, v6, v0
	v_lshrrev_b32_e32 v6, 3, v215
	s_movk_i32 s2, 0x70
	s_addc_u32 s27, s75, 0
	v_and_or_b32 v7, v6, s2, v3
	s_movk_i32 s2, 0x60
	v_add_u32_e32 v2, 0x2000, v2
	s_add_u32 s28, s74, 0x1300000
	v_and_or_b32 v6, v6, s2, v5
	v_lshrrev_b32_e32 v2, 7, v2
	s_movk_i32 s2, 0xf0
	s_mul_i32 s18, s1, 0x580
	s_addc_u32 s29, s75, 0
	v_and_or_b32 v3, v2, s2, v3
	s_movk_i32 s2, 0xe0
	s_ashr_i32 s19, s18, 31
	v_and_or_b32 v2, v2, s2, v5
	s_lshl_b64 s[2:3], s[18:19], 1
	s_add_u32 s5, s28, s2
	s_addc_u32 s6, s29, s3
	s_add_u32 s7, s26, s2
	s_addc_u32 s8, s27, s3
	s_lshr_b32 s4, s0, 6
	s_lshr_b32 s1, s0, 8
	s_lshl_b32 s30, s4, 10
	s_mul_i32 s3, s44, 0x160000
	v_mul_u32_u24_e32 v6, 0xb00, v6
	s_mul_hi_i32 s2, s44, 0x160000
	s_add_u32 s20, s5, s3
	v_or_b32_e32 v6, v6, v4
	s_addc_u32 s21, s6, s2
	s_add_i32 s31, s30, 0
	v_lshlrev_b32_e32 v130, 1, v6
	v_mul_u32_u24_e32 v2, 0xb00, v2
	s_add_i32 m0, s31, 0x10000
	v_or_b32_e32 v2, v2, v4
	global_load_lds_dwordx4 v130, s[20:21]
	s_add_i32 m0, s31, 0x12000
	v_lshlrev_b32_e32 v134, 1, v2
	s_add_u32 s2, s20, 0xb0000
	global_load_lds_dwordx4 v134, s[20:21]
	s_addc_u32 s3, s21, 0
	s_add_i32 m0, s31, 0x14000
	s_mul_i32 s10, s45, 0x160000
	global_load_lds_dwordx4 v130, s[2:3]
	s_add_i32 m0, s31, 0x16000
	v_mul_u32_u24_e32 v11, 0xb00, v7
	s_mul_hi_i32 s9, s45, 0x160000
	global_load_lds_dwordx4 v134, s[2:3]
	s_add_u32 s2, s7, s10
	v_or_b32_e32 v7, v4, v11
	v_mul_u32_u24_e32 v12, 0xb00, v3
	s_addc_u32 s3, s8, s9
	s_add_i32 s33, s31, 0x2000
	v_lshlrev_b32_e32 v128, 1, v7
	v_or_b32_e32 v3, v12, v4
	s_mov_b32 m0, s31
	s_add_u32 s6, s2, 0xb0000
	v_lshlrev_b32_e32 v132, 1, v3
	global_load_lds_dwordx4 v128, s[2:3]
	s_mov_b32 m0, s33
	s_addc_u32 s7, s3, 0
	s_add_i32 s34, s31, 0x4000
	global_load_lds_dwordx4 v132, s[2:3]
	s_mov_b32 m0, s34
	s_add_i32 s35, s31, 0x6000
	global_load_lds_dwordx4 v128, s[6:7]
	s_mov_b32 m0, s35
	v_mov_b32_e32 v137, 0
	global_load_lds_dwordx4 v132, s[6:7]
	v_mov_b32_e32 v131, v137
	v_mov_b32_e32 v135, v137
	v_mov_b32_e32 v129, v137
	v_mov_b32_e32 v133, v137
	s_cmp_eq_u32 s1, 1
	s_mov_b32 s5, 0
	v_lshl_add_u64 v[8:9], s[20:21], 0, v[130:131]
	v_lshl_add_u64 v[6:7], s[20:21], 0, v[134:135]
	v_lshl_add_u64 v[2:3], s[2:3], 0, v[128:129]
	s_cselect_b64 s[6:7], -1, 0
	s_cmp_lg_u32 s1, 1
	v_lshl_add_u64 v[4:5], s[2:3], 0, v[132:133]
	s_cbranch_scc1 .LBB0_1423
	s_barrier
